# group barriers at SEAM 6/7/8 + run-time XCD co-location check with fallback to the grid barrier
# baseline (speedup 1.0000x reference)
_Z14fwd_megakernel4Args:
	s_load_dwordx8 s[84:91], s[0:1], 0xc0
	s_load_dwordx4 s[92:95], s[0:1], 0xe0
	s_load_dword s3, s[0:1], 0xf0
	s_add_u32 s4, s0, 0xf0
	s_addc_u32 s5, s1, 0
	v_readfirstlane_b32 s97, v0
	v_writelane_b32 v246, s4, 0
	v_cmp_gt_u32_e32 vcc, 2, v0
	s_nop 0
	v_writelane_b32 v246, s5, 1
	s_and_saveexec_b64 s[4:5], vcc
	v_lshl_add_u32 v1, v0, 2, 0
	v_add_u32_e32 v1, 0x22000, v1
	v_mov_b32_e32 v2, 0
	ds_write_b32 v1, v2
	s_or_b64 exec, exec, s[4:5]
	s_waitcnt lgkmcnt(0)
	s_barrier
	s_getreg_b32 s4, hwreg(HW_REG_XCC_ID, 0, 4)
	s_and_b32 s33, s4, 15
	v_cmp_eq_u32_e64 s[6:7], 0, v0
	s_mov_b64 s[4:5], exec
	s_nop 0
	v_writelane_b32 v246, s6, 2
	s_nop 1
	v_writelane_b32 v246, s7, 3
	s_and_b64 s[6:7], s[4:5], s[6:7]
	s_mov_b64 exec, s[6:7]
	s_cbranch_execz .LBB0_5
	s_mov_b64 s[6:7], exec
	v_mbcnt_lo_u32_b32 v1, s6, 0
	v_mbcnt_hi_u32_b32 v1, s7, v1
	v_cmp_eq_u32_e32 vcc, 0, v1
	s_and_b64 s[8:9], exec, vcc
	s_mov_b64 exec, s[8:9]
	s_cbranch_execz .LBB0_5
	s_lshl_b32 s8, s33, 8
	s_bcnt1_i32_b64 s6, s[6:7]
	v_mov_b32_e32 v1, s8
	v_mov_b32_e32 v2, s6
	global_atomic_add v1, v2, s[92:93] offset:1024
	s_and_b32 s8, s2, 15
	s_lshl_b32 s8, s8, 2
	s_add_u32 s8, s8, 0x54200
	s_add_u32 s10, s92, s8
	s_addc_u32 s11, s93, 0
	s_lshl_b32 s9, 1, s33
	v_mov_b32_e32 v3, 0
	v_mov_b32_e32 v4, s9
	global_atomic_or v3, v4, s[10:11]

.LBB0_207:
	s_mov_b64 s[8:9], exec
	s_lshl_b32 s6, s33, 8
	v_mbcnt_lo_u32_b32 v3, s8, 0
	s_add_u32 s6, s92, s6
	v_mbcnt_hi_u32_b32 v3, s9, v3
	s_addc_u32 s7, s93, 0
	v_cmp_eq_u32_e32 vcc, 0, v3
	s_and_saveexec_b64 s[10:11], vcc
	s_cbranch_execz .LBB0_209
	s_and_b32 s100, s2, 15
	s_lshl_b32 s100, s100, 2
	s_add_u32 s100, s100, 0x54200
	s_add_u32 s100, s92, s100
	s_addc_u32 s101, s93, 0
	v_mov_b32_e32 v18, 0
	global_load_dword v19, v18, s[100:101] sc1
	s_bcnt1_i32_b64 s8, s[8:9]
	v_mov_b32_e32 v5, 0x1000
	v_mov_b32_e32 v6, s8
	global_atomic_add v5, v5, v6, s[6:7] offset:1024 sc0
.LBB0_209:
	s_or_b64 exec, exec, s[10:11]
	v_cvt_f32_u32_e32 v6, v4
	s_waitcnt vmcnt(0)
	v_readfirstlane_b32 s8, v5
	v_add_u32_e32 v18, -1, v19
	v_and_b32_e32 v18, v18, v19
	v_cmp_ne_u32_e32 vcc, 0, v18
	s_and_saveexec_b64 s[100:101], vcc
	s_cbranch_execz .Lcoloc_ok
	s_add_u32 s98, s92, 0x54100
	s_addc_u32 s99, s93, 0
	v_mov_b32_e32 v18, 0
	v_mov_b32_e32 v19, 1
	global_atomic_add v18, v19, s[98:99]
.Lcoloc_ok:
	s_or_b64 exec, exec, s[100:101]
	v_sub_u32_e32 v5, 0, v4
	v_rcp_iflag_f32_e32 v6, v6
	v_add_u32_e32 v7, s8, v3
	v_mul_f32_e32 v6, 0x4f7ffffe, v6
	v_cvt_u32_f32_e32 v6, v6
	v_mul_lo_u32 v3, v5, v6
	v_mul_hi_u32 v3, v6, v3
	v_add_u32_e32 v3, v6, v3
	v_mul_hi_u32 v3, v7, v3
	v_mul_lo_u32 v5, v3, v4
	v_sub_u32_e32 v5, v7, v5
	v_add_u32_e32 v6, 1, v3
	v_cmp_ge_u32_e32 vcc, v5, v4
	s_nop 1
	v_cndmask_b32_e32 v3, v3, v6, vcc
	v_sub_u32_e32 v6, v5, v4
	v_cndmask_b32_e32 v5, v5, v6, vcc
	v_add_u32_e32 v6, 1, v3
	v_cmp_ge_u32_e32 vcc, v5, v4
	v_add_u32_e32 v5, 1, v7
	s_nop 0
	v_cndmask_b32_e32 v3, v3, v6, vcc
	v_mul_lo_u32 v6, v4, v3
	v_add_u32_e32 v4, v6, v4
	v_cmp_ne_u32_e32 vcc, v5, v4
	s_and_saveexec_b64 s[8:9], vcc
	s_xor_b64 s[8:9], exec, s[8:9]
	s_cbranch_execz .LBB0_223
	s_waitcnt lgkmcnt(0)
	v_mov_b32_e32 v2, 0x2000
	global_load_dword v2, v2, s[6:7] offset:1024 sc1
	s_add_u32 s14, s6, 0x2400
	s_addc_u32 s15, s7, 0
	s_waitcnt vmcnt(0)
	v_cmp_eq_u32_e32 vcc, v2, v3
	s_and_saveexec_b64 s[10:11], vcc
	s_cbranch_execz .LBB0_222
	s_mov_b32 s26, 1
	s_mov_b64 s[16:17], 0
	v_mov_b32_e32 v2, 0
	s_branch .LBB0_213

.LBB0_629:
	s_cmp_gt_i32 s95, 7
	s_cselect_b64 s[0:1], -1, 0
	s_and_b64 s[4:5], s[4:5], s[0:1]
	s_andn2_b64 vcc, exec, s[4:5]
	s_cbranch_vccnz .LBB0_683
	s_waitcnt vmcnt(0)
	s_waitcnt vmcnt(0)
	s_barrier
	s_mov_b64 s[4:5], exec
	v_readlane_b32 s6, v246, 2
	v_readlane_b32 s7, v246, 3
	s_and_b64 s[6:7], s[4:5], s[6:7]
	s_mov_b64 exec, s[6:7]
	s_cbranch_execz .LBB0_682
	s_and_b32 s6, s2, 15
	s_lshl_b32 s6, s6, 8
	s_add_u32 s6, s92, s6
	s_addc_u32 s7, s93, 0
	s_add_u32 s6, s6, 0x53000
	s_addc_u32 s7, s7, 0
	s_add_u32 s8, s92, 0x54000
	s_addc_u32 s9, s93, 0
	v_mov_b32_e32 v1, 0
	v_mov_b32_e32 v2, 1
	global_atomic_add v1, v2, s[6:7]
	s_mov_b32 s10, 0x400000
	s_movk_i32 s11, 15
	global_atomic_add v1, v2, s[8:9]
	global_load_dword v4, v1, s[8:9] offset:256 sc1
	global_load_dword v3, v1, s[6:7] sc1
	s_waitcnt vmcnt(0)
	v_readfirstlane_b32 s98, v4
	s_cmp_lg_u32 s98, 0
	s_cbranch_scc1 .Lgb6_orig
	v_cmp_lt_u32_e32 vcc, s11, v3
	s_cbranch_vccnz .Lgb6_ok

.Lgb6_orig:
	s_add_i32 s6, 0, 0x22000
	v_mov_b32_e32 v1, s6
	s_waitcnt vmcnt(0) expcnt(0) lgkmcnt(0)
	ds_read_b32 v3, v1
	s_add_i32 s6, 0, 0x22004
	v_mov_b32_e32 v1, s6
	ds_read_b32 v1, v1
	s_waitcnt lgkmcnt(1)
	v_cmp_ne_u32_e32 vcc, 0, v3
	s_cbranch_vccnz .LBB0_646
	v_readlane_b32 s6, v246, 0
	v_readlane_b32 s7, v246, 1
	s_load_dwordx2 s[10:11], s[6:7], 0x4
	s_add_u32 s6, s92, 0x1000
	s_addc_u32 s7, s93, 0
	s_add_u32 s8, s92, 0x1100
	s_addc_u32 s9, s93, 0
	s_waitcnt lgkmcnt(0)
	s_mul_i32 s20, s10, s3
	s_add_u32 s10, s92, 0x1200
	s_mul_i32 s20, s20, s11
	s_addc_u32 s11, s93, 0
	s_add_u32 s12, s92, 0x1300
	s_addc_u32 s13, s93, 0
	s_mov_b32 s21, 1
	v_mov_b32_e32 v17, 0
	s_branch .LBB0_634

.LBB0_761:
	s_cmp_gt_i32 s95, 8
	s_cselect_b64 s[0:1], -1, 0
	s_and_b64 s[4:5], s[6:7], s[0:1]
	s_andn2_b64 vcc, exec, s[4:5]
	s_cbranch_vccnz .LBB0_815
	s_waitcnt vmcnt(0)
	s_waitcnt vmcnt(0)
	s_barrier
	s_mov_b64 s[4:5], exec
	v_readlane_b32 s6, v246, 2
	v_readlane_b32 s7, v246, 3
	s_and_b64 s[6:7], s[4:5], s[6:7]
	s_mov_b64 exec, s[6:7]
	s_cbranch_execz .LBB0_814
	s_cmp_lg_u32 s98, 0
	s_cbranch_scc1 .Lgb7_orig
	s_and_b32 s6, s2, 15
	s_lshl_b32 s6, s6, 8
	s_add_u32 s6, s92, s6
	s_addc_u32 s7, s93, 0
	s_add_u32 s6, s6, 0x53000
	s_addc_u32 s7, s7, 0
	s_add_u32 s8, s92, 0x54000
	s_addc_u32 s9, s93, 0
	v_mov_b32_e32 v1, 0
	v_mov_b32_e32 v2, 1
	global_atomic_add v1, v2, s[6:7]
	s_mov_b32 s10, 0x400000
	s_movk_i32 s11, 31

.LBB0_836:
	s_cmp_gt_i32 s95, 9
	s_cselect_b64 s[0:1], -1, 0
	s_and_b64 s[4:5], s[4:5], s[0:1]
	s_andn2_b64 vcc, exec, s[4:5]
	s_cbranch_vccnz .LBB0_890
	s_waitcnt vmcnt(0)
	s_waitcnt vmcnt(0)
	s_barrier
	s_mov_b64 s[4:5], exec
	v_readlane_b32 s6, v246, 2
	v_readlane_b32 s7, v246, 3
	s_and_b64 s[6:7], s[4:5], s[6:7]
	s_mov_b64 exec, s[6:7]
	s_cbranch_execz .LBB0_889
	s_cmp_lg_u32 s98, 0
	s_cbranch_scc1 .Lgb8_orig
	s_and_b32 s6, s2, 15
	s_lshl_b32 s6, s6, 8
	s_add_u32 s6, s92, s6
	s_addc_u32 s7, s93, 0
	s_add_u32 s6, s6, 0x53000
	s_addc_u32 s7, s7, 0
	s_add_u32 s8, s92, 0x54000
	s_addc_u32 s9, s93, 0
	v_mov_b32_e32 v1, 0
	v_mov_b32_e32 v2, 1
	global_atomic_add v1, v2, s[6:7]
	s_mov_b32 s10, 0x400000
	s_movk_i32 s11, 47

	.amdhsa_kernel _Z14fwd_megakernel4Args
		.amdhsa_group_segment_fixed_size 0
		.amdhsa_private_segment_fixed_size 0
		.amdhsa_kernarg_size 496
		.amdhsa_user_sgpr_count 2
		.amdhsa_user_sgpr_dispatch_ptr 0
		.amdhsa_user_sgpr_queue_ptr 0
		.amdhsa_user_sgpr_kernarg_segment_ptr 1
		.amdhsa_user_sgpr_dispatch_id 0
		.amdhsa_user_sgpr_kernarg_preload_length 0
		.amdhsa_user_sgpr_kernarg_preload_offset 0
		.amdhsa_user_sgpr_private_segment_size 0
		.amdhsa_uses_dynamic_stack 0
		.amdhsa_enable_private_segment 0
		.amdhsa_system_sgpr_workgroup_id_x 1
		.amdhsa_system_sgpr_workgroup_id_y 0
		.amdhsa_system_sgpr_workgroup_id_z 0
		.amdhsa_system_sgpr_workgroup_info 0
		.amdhsa_system_vgpr_workitem_id 0
		.amdhsa_next_free_vgpr 256
		.amdhsa_next_free_sgpr 102
		.amdhsa_accum_offset 256
		.amdhsa_reserve_vcc 1
		.amdhsa_float_round_mode_32 0
		.amdhsa_float_round_mode_16_64 0
		.amdhsa_float_denorm_mode_32 3
		.amdhsa_float_denorm_mode_16_64 3
		.amdhsa_dx10_clamp 1
		.amdhsa_ieee_mode 1
		.amdhsa_fp16_overflow 0
		.amdhsa_tg_split 0
		.amdhsa_exception_fp_ieee_invalid_op 0
		.amdhsa_exception_fp_denorm_src 0
		.amdhsa_exception_fp_ieee_div_zero 0
		.amdhsa_exception_fp_ieee_overflow 0
		.amdhsa_exception_fp_ieee_underflow 0
		.amdhsa_exception_fp_ieee_inexact 0
		.amdhsa_exception_int_div_zero 0
	.end_amdhsa_kernel

amdhsa.kernels:
  - .agpr_count:     0
    .args:
      - .offset:         0
        .size:           240
        .value_kind:     by_value
      - .offset:         240
        .size:           4
        .value_kind:     hidden_block_count_x
      - .offset:         244
        .size:           4
        .value_kind:     hidden_block_count_y
      - .offset:         248
        .size:           4
        .value_kind:     hidden_block_count_z
      - .offset:         252
        .size:           2
        .value_kind:     hidden_group_size_x
      - .offset:         254
        .size:           2
        .value_kind:     hidden_group_size_y
      - .offset:         256
        .size:           2
        .value_kind:     hidden_group_size_z
      - .offset:         258
        .size:           2
        .value_kind:     hidden_remainder_x
      - .offset:         260
        .size:           2
        .value_kind:     hidden_remainder_y
      - .offset:         262
        .size:           2
        .value_kind:     hidden_remainder_z
      - .offset:         280
        .size:           8
        .value_kind:     hidden_global_offset_x
      - .offset:         288
        .size:           8
        .value_kind:     hidden_global_offset_y
      - .offset:         296
        .size:           8
        .value_kind:     hidden_global_offset_z
      - .offset:         304
        .size:           2
        .value_kind:     hidden_grid_dims
      - .offset:         360
        .size:           4
        .value_kind:     hidden_dynamic_lds_size
    .group_segment_fixed_size: 0
    .kernarg_segment_align: 8
    .kernarg_segment_size: 496
    .language:       OpenCL C
    .language_version:
      - 2
      - 0
    .max_flat_workgroup_size: 512
    .name:           _Z14fwd_megakernel4Args
    .private_segment_fixed_size: 0
    .sgpr_count:     108
    .sgpr_spill_count: 4
    .symbol:         _Z14fwd_megakernel4Args.kd
    .uniform_work_group_size: 1
    .uses_dynamic_stack: false
    .vgpr_count:     256
    .vgpr_spill_count: 0
    .wavefront_size: 64
